# inproj rotary-key epilogue: each group of 32 two-byte stores (4 consecutive channels x {o1,o2} x 4 heads) packed into 8 eight-byte stores
# speedup vs baseline: 1.0082x; 1.0082x over previous
; DI void phase_inproj(const Prm& p, unsigned char* smem_raw, int l, int S, int& base) {
;     ...
;               } else if (nb < 4192) {
;                 if (nb == 4160) {
;                   const f32x4 v2 = acc[ai][bj][(m + 1) & 3][n];
;                   const int pos = tok & (S - 1);
; #pragma unroll
;                   for (int j = 0; j < 4; ++j) {
;                     const int ii = fq * 4 + j;
;                     const float2 cs = p.rope[pos * 16 + ii];
;                     const u16 o1 = f2bf(v[j] * cs.x - v2[j] * cs.y), o2 = f2bf(v[j] * cs.y + v2[j] * cs.x);
; #pragma unroll
;                     for (int hh = 0; hh < 4; ++hh) {
;                       p.kc[(size_t)tok * 384 + hh * 96 + 64 + ii] = o1;
;                       p.kc[(size_t)tok * 384 + hh * 96 + 80 + ii] = o2;
;                     }
;                   }
;                 }
.LBB0_605:
	s_andn2_b64 vcc, exec, s[2:3]
	s_cbranch_vccnz .LBB0_608
	s_andn2_b64 vcc, exec, s[4:5]
	s_cbranch_vccnz .LBB0_608
	v_readlane_b32 s36, v252, 0
	v_readlane_b32 s2, v254, 45
	v_readlane_b32 s37, v252, 1
	v_readlane_b32 s38, v252, 2
	v_readlane_b32 s39, v252, 3
	v_readlane_b32 s40, v252, 4
	v_readlane_b32 s41, v252, 5
	v_readlane_b32 s42, v252, 6
	v_readlane_b32 s43, v252, 7
	v_and_b32_e32 v131, s2, v130
	v_mov_b64_e32 v[134:135], s[36:37]
	v_readlane_b32 s36, v253, 8
	v_lshl_or_b32 v136, v131, 4, v132
	v_mov_b32_e32 v137, v1
	v_readlane_b32 s40, v253, 12
	v_readlane_b32 s41, v253, 13
	v_mad_i64_i32 v[134:135], s[2:3], v130, s33, v[134:135]
	s_nop 0
	v_lshl_add_u64 v[136:137], v[136:137], 3, s[40:41]
	global_load_dwordx2 v[144:145], v[136:137], off
	global_load_dwordx2 v[146:147], v[136:137], off offset:8
	global_load_dwordx2 v[148:149], v[136:137], off offset:16
	global_load_dwordx2 v[150:151], v[136:137], off offset:24
	v_readlane_b32 s37, v253, 9
	v_readlane_b32 s38, v253, 10
	v_readlane_b32 s39, v253, 11
	v_readlane_b32 s42, v253, 14
	v_readlane_b32 s43, v253, 15
	v_readlane_b32 s44, v253, 16
	v_readlane_b32 s45, v253, 17
	v_readlane_b32 s46, v253, 18
	v_readlane_b32 s47, v253, 19
	v_readlane_b32 s48, v253, 20
	v_readlane_b32 s49, v253, 21
	v_readlane_b32 s50, v253, 22
	v_readlane_b32 s51, v253, 23
	s_waitcnt vmcnt(0)
	v_lshlrev_b32_e32 v136, 1, v132
	v_mov_b32_e32 v137, v1
	v_lshl_add_u64 v[134:135], v[134:135], 0, v[136:137]
	v_mul_f32_e32 v131, v110, v145
	v_mul_f32_e32 v145, v126, v145
	v_fmac_f32_e32 v145, v110, v144
	v_fma_f32 v144, v126, v144, -v131
	v_mul_f32_e32 v131, v111, v147
	v_mul_f32_e32 v147, v127, v147
	v_fmac_f32_e32 v147, v111, v146
	v_fma_f32 v146, v127, v146, -v131
	v_mul_f32_e32 v131, v112, v149
	v_mul_f32_e32 v149, v128, v149
	v_fmac_f32_e32 v149, v112, v148
	v_fma_f32 v148, v128, v148, -v131
	v_mul_f32_e32 v131, v113, v151
	v_mul_f32_e32 v151, v129, v151
	v_fmac_f32_e32 v151, v113, v150
	v_fma_f32 v150, v129, v150, -v131
	v_cvt_pk_bf16_f32 v131, v144, v146
	v_cvt_pk_bf16_f32 v144, v145, v147
	v_cvt_pk_bf16_f32 v145, v149, v151
	v_cvt_pk_bf16_f32 v147, v148, v150
	v_mov_b32_e32 v146, v131
	global_store_dwordx2 v[134:135], v[146:147], off offset:128
	global_store_dwordx2 v[134:135], v[144:145], off offset:160
	global_store_dwordx2 v[134:135], v[146:147], off offset:320
	global_store_dwordx2 v[134:135], v[144:145], off offset:352
	global_store_dwordx2 v[134:135], v[146:147], off offset:512
	global_store_dwordx2 v[134:135], v[144:145], off offset:544
	global_store_dwordx2 v[134:135], v[146:147], off offset:704
	global_store_dwordx2 v[134:135], v[144:145], off offset:736

; DI void phase_inproj(const Prm& p, unsigned char* smem_raw, int l, int S, int& base) {
;     ...
;               } else if (nb < 4192) {
;                 if (nb == 4160) {
;                   const f32x4 v2 = acc[ai][bj][(m + 1) & 3][n];
;                   const int pos = tok & (S - 1);
; #pragma unroll
;                   for (int j = 0; j < 4; ++j) {
;                     const int ii = fq * 4 + j;
;                     const float2 cs = p.rope[pos * 16 + ii];
;                     const u16 o1 = f2bf(v[j] * cs.x - v2[j] * cs.y), o2 = f2bf(v[j] * cs.y + v2[j] * cs.x);
; #pragma unroll
;                     for (int hh = 0; hh < 4; ++hh) {
;                       p.kc[(size_t)tok * 384 + hh * 96 + 64 + ii] = o1;
;                       p.kc[(size_t)tok * 384 + hh * 96 + 80 + ii] = o2;
;                     }
;                   }
;                 }
.LBB0_639:
	s_andn2_b64 vcc, exec, s[0:1]
	s_cbranch_vccnz .LBB0_642
	s_andn2_b64 vcc, exec, s[4:5]
	s_cbranch_vccnz .LBB0_642
	v_readlane_b32 s0, v254, 45
	v_mov_b32_e32 v125, v1
	s_nop 0
	v_and_b32_e32 v119, s0, v118
	v_readlane_b32 s0, v252, 0
	v_readlane_b32 s1, v252, 1
	v_readlane_b32 s2, v252, 2
	v_readlane_b32 s3, v252, 3
	v_mov_b64_e32 v[120:121], s[0:1]
	v_readlane_b32 s4, v252, 4
	v_readlane_b32 s5, v252, 5
	v_readlane_b32 s6, v252, 6
	v_readlane_b32 s7, v252, 7
	v_mad_i64_i32 v[120:121], s[0:1], v118, s33, v[120:121]
	v_readlane_b32 s0, v253, 8
	v_lshl_or_b32 v124, v119, 4, v132
	v_readlane_b32 s4, v253, 12
	v_readlane_b32 s5, v253, 13
	v_readlane_b32 s1, v253, 9
	v_readlane_b32 s2, v253, 10
	v_lshl_add_u64 v[124:125], v[124:125], 3, s[4:5]
	global_load_dwordx2 v[144:145], v[124:125], off
	global_load_dwordx2 v[146:147], v[124:125], off offset:8
	global_load_dwordx2 v[148:149], v[124:125], off offset:16
	global_load_dwordx2 v[150:151], v[124:125], off offset:24
	v_readlane_b32 s3, v253, 11
	v_readlane_b32 s6, v253, 14
	v_readlane_b32 s7, v253, 15
	v_readlane_b32 s8, v253, 16
	v_readlane_b32 s9, v253, 17
	v_readlane_b32 s10, v253, 18
	v_readlane_b32 s11, v253, 19
	v_readlane_b32 s12, v253, 20
	v_readlane_b32 s13, v253, 21
	v_readlane_b32 s14, v253, 22
	v_readlane_b32 s15, v253, 23
	s_waitcnt vmcnt(0)
	v_lshlrev_b32_e32 v124, 1, v132
	v_mov_b32_e32 v125, v1
	v_lshl_add_u64 v[120:121], v[120:121], 0, v[124:125]
	v_mul_f32_e32 v119, v98, v145
	v_mul_f32_e32 v145, v114, v145
	v_fmac_f32_e32 v145, v98, v144
	v_fma_f32 v144, v114, v144, -v119
	v_mul_f32_e32 v119, v99, v147
	v_mul_f32_e32 v147, v115, v147
	v_fmac_f32_e32 v147, v99, v146
	v_fma_f32 v146, v115, v146, -v119
	v_mul_f32_e32 v119, v100, v149
	v_mul_f32_e32 v149, v116, v149
	v_fmac_f32_e32 v149, v100, v148
	v_fma_f32 v148, v116, v148, -v119
	v_mul_f32_e32 v119, v101, v151
	v_mul_f32_e32 v151, v117, v151
	v_fmac_f32_e32 v151, v101, v150
	v_fma_f32 v150, v117, v150, -v119
	v_cvt_pk_bf16_f32 v119, v144, v146
	v_cvt_pk_bf16_f32 v144, v145, v147
	v_cvt_pk_bf16_f32 v145, v149, v151
	v_cvt_pk_bf16_f32 v147, v148, v150
	v_mov_b32_e32 v146, v119
	global_store_dwordx2 v[120:121], v[146:147], off offset:128
	global_store_dwordx2 v[120:121], v[144:145], off offset:160
	global_store_dwordx2 v[120:121], v[146:147], off offset:320
	global_store_dwordx2 v[120:121], v[144:145], off offset:352
	global_store_dwordx2 v[120:121], v[146:147], off offset:512
	global_store_dwordx2 v[120:121], v[144:145], off offset:544
	global_store_dwordx2 v[120:121], v[146:147], off offset:704
	global_store_dwordx2 v[120:121], v[144:145], off offset:736

; DI void phase_inproj(const Prm& p, unsigned char* smem_raw, int l, int S, int& base) {
;     ...
;               } else if (nb < 4192) {
;                 if (nb == 4160) {
;                   const f32x4 v2 = acc[ai][bj][(m + 1) & 3][n];
;                   const int pos = tok & (S - 1);
; #pragma unroll
;                   for (int j = 0; j < 4; ++j) {
;                     const int ii = fq * 4 + j;
;                     const float2 cs = p.rope[pos * 16 + ii];
;                     const u16 o1 = f2bf(v[j] * cs.x - v2[j] * cs.y), o2 = f2bf(v[j] * cs.y + v2[j] * cs.x);
; #pragma unroll
;                     for (int hh = 0; hh < 4; ++hh) {
;                       p.kc[(size_t)tok * 384 + hh * 96 + 64 + ii] = o1;
;                       p.kc[(size_t)tok * 384 + hh * 96 + 80 + ii] = o2;
;                     }
;                   }
;                 }
.LBB0_767:
	s_andn2_b64 vcc, exec, s[0:1]
	s_cbranch_vccnz .LBB0_770
	s_andn2_b64 vcc, exec, s[4:5]
	s_cbranch_vccnz .LBB0_770
	v_readlane_b32 s36, v252, 0
	v_readlane_b32 s0, v254, 45
	v_readlane_b32 s37, v252, 1
	v_readlane_b32 s38, v252, 2
	v_readlane_b32 s39, v252, 3
	v_readlane_b32 s40, v252, 4
	v_readlane_b32 s41, v252, 5
	v_readlane_b32 s42, v252, 6
	v_readlane_b32 s43, v252, 7
	v_and_b32_e32 v67, s0, v130
	v_mov_b64_e32 v[68:69], s[36:37]
	v_readlane_b32 s36, v253, 8
	v_lshl_or_b32 v70, v67, 4, v132
	v_mov_b32_e32 v71, v1
	v_readlane_b32 s40, v253, 12
	v_readlane_b32 s41, v253, 13
	v_mad_i64_i32 v[68:69], s[0:1], v130, s33, v[68:69]
	s_nop 0
	v_lshl_add_u64 v[70:71], v[70:71], 3, s[40:41]
	global_load_dwordx2 v[144:145], v[70:71], off
	global_load_dwordx2 v[146:147], v[70:71], off offset:8
	global_load_dwordx2 v[148:149], v[70:71], off offset:16
	global_load_dwordx2 v[150:151], v[70:71], off offset:24
	v_readlane_b32 s37, v253, 9
	v_readlane_b32 s38, v253, 10
	v_readlane_b32 s39, v253, 11
	v_readlane_b32 s42, v253, 14
	v_readlane_b32 s43, v253, 15
	v_readlane_b32 s44, v253, 16
	v_readlane_b32 s45, v253, 17
	v_readlane_b32 s46, v253, 18
	v_readlane_b32 s47, v253, 19
	v_readlane_b32 s48, v253, 20
	v_readlane_b32 s49, v253, 21
	v_readlane_b32 s50, v253, 22
	v_readlane_b32 s51, v253, 23
	s_waitcnt vmcnt(0)
	v_lshlrev_b32_e32 v70, 1, v132
	v_mov_b32_e32 v71, v1
	v_lshl_add_u64 v[68:69], v[68:69], 0, v[70:71]
	v_mul_f32_e32 v67, v46, v145
	v_mul_f32_e32 v145, v62, v145
	v_fmac_f32_e32 v145, v46, v144
	v_fma_f32 v144, v62, v144, -v67
	v_mul_f32_e32 v67, v47, v147
	v_mul_f32_e32 v147, v63, v147
	v_fmac_f32_e32 v147, v47, v146
	v_fma_f32 v146, v63, v146, -v67
	v_mul_f32_e32 v67, v48, v149
	v_mul_f32_e32 v149, v64, v149
	v_fmac_f32_e32 v149, v48, v148
	v_fma_f32 v148, v64, v148, -v67
	v_mul_f32_e32 v67, v49, v151
	v_mul_f32_e32 v151, v65, v151
	v_fmac_f32_e32 v151, v49, v150
	v_fma_f32 v150, v65, v150, -v67
	v_cvt_pk_bf16_f32 v67, v144, v146
	v_cvt_pk_bf16_f32 v144, v145, v147
	v_cvt_pk_bf16_f32 v145, v149, v151
	v_cvt_pk_bf16_f32 v147, v148, v150
	v_mov_b32_e32 v146, v67
	global_store_dwordx2 v[68:69], v[146:147], off offset:128
	global_store_dwordx2 v[68:69], v[144:145], off offset:160
	global_store_dwordx2 v[68:69], v[146:147], off offset:320
	global_store_dwordx2 v[68:69], v[144:145], off offset:352
	global_store_dwordx2 v[68:69], v[146:147], off offset:512
	global_store_dwordx2 v[68:69], v[144:145], off offset:544
	global_store_dwordx2 v[68:69], v[146:147], off offset:704
	global_store_dwordx2 v[68:69], v[144:145], off offset:736

; DI void phase_inproj(const Prm& p, unsigned char* smem_raw, int l, int S, int& base) {
;     ...
;               } else if (nb < 4192) {
;                 if (nb == 4160) {
;                   const f32x4 v2 = acc[ai][bj][(m + 1) & 3][n];
;                   const int pos = tok & (S - 1);
; #pragma unroll
;                   for (int j = 0; j < 4; ++j) {
;                     const int ii = fq * 4 + j;
;                     const float2 cs = p.rope[pos * 16 + ii];
;                     const u16 o1 = f2bf(v[j] * cs.x - v2[j] * cs.y), o2 = f2bf(v[j] * cs.y + v2[j] * cs.x);
; #pragma unroll
;                     for (int hh = 0; hh < 4; ++hh) {
;                       p.kc[(size_t)tok * 384 + hh * 96 + 64 + ii] = o1;
;                       p.kc[(size_t)tok * 384 + hh * 96 + 80 + ii] = o2;
;                     }
;                   }
;                 }
.LBB0_1135:
	s_andn2_b64 vcc, exec, s[52:53]
	s_cbranch_vccnz .LBB0_1138
	s_andn2_b64 vcc, exec, s[4:5]
	s_cbranch_vccnz .LBB0_1138
	v_readlane_b32 s36, v252, 0
	v_readlane_b32 s8, v254, 45
	v_readlane_b32 s37, v252, 1
	v_readlane_b32 s38, v252, 2
	v_readlane_b32 s39, v252, 3
	v_readlane_b32 s40, v252, 4
	v_readlane_b32 s41, v252, 5
	v_readlane_b32 s42, v252, 6
	v_readlane_b32 s43, v252, 7
	v_and_b32_e32 v127, s8, v126
	v_mov_b64_e32 v[128:129], s[36:37]
	v_readlane_b32 s36, v253, 8
	v_lshl_or_b32 v138, v127, 4, v132
	v_mov_b32_e32 v139, v1
	v_readlane_b32 s40, v253, 12
	v_readlane_b32 s41, v253, 13
	v_mad_i64_i32 v[128:129], s[52:53], v126, s33, v[128:129]
	s_nop 0
	v_lshl_add_u64 v[138:139], v[138:139], 3, s[40:41]
	global_load_dwordx2 v[144:145], v[138:139], off
	global_load_dwordx2 v[146:147], v[138:139], off offset:8
	global_load_dwordx2 v[148:149], v[138:139], off offset:16
	global_load_dwordx2 v[150:151], v[138:139], off offset:24
	v_readlane_b32 s37, v253, 9
	v_readlane_b32 s38, v253, 10
	v_readlane_b32 s39, v253, 11
	v_readlane_b32 s42, v253, 14
	v_readlane_b32 s43, v253, 15
	v_readlane_b32 s44, v253, 16
	v_readlane_b32 s45, v253, 17
	v_readlane_b32 s46, v253, 18
	v_readlane_b32 s47, v253, 19
	v_readlane_b32 s48, v253, 20
	v_readlane_b32 s49, v253, 21
	v_readlane_b32 s50, v253, 22
	v_readlane_b32 s51, v253, 23
	s_waitcnt vmcnt(0)
	v_lshlrev_b32_e32 v138, 1, v132
	v_mov_b32_e32 v139, v1
	v_lshl_add_u64 v[128:129], v[128:129], 0, v[138:139]
	v_mul_f32_e32 v127, v106, v145
	v_mul_f32_e32 v145, v122, v145
	v_fmac_f32_e32 v145, v106, v144
	v_fma_f32 v144, v122, v144, -v127
	v_mul_f32_e32 v127, v107, v147
	v_mul_f32_e32 v147, v123, v147
	v_fmac_f32_e32 v147, v107, v146
	v_fma_f32 v146, v123, v146, -v127
	v_mul_f32_e32 v127, v108, v149
	v_mul_f32_e32 v149, v124, v149
	v_fmac_f32_e32 v149, v108, v148
	v_fma_f32 v148, v124, v148, -v127
	v_mul_f32_e32 v127, v109, v151
	v_mul_f32_e32 v151, v125, v151
	v_fmac_f32_e32 v151, v109, v150
	v_fma_f32 v150, v125, v150, -v127
	v_cvt_pk_bf16_f32 v127, v144, v146
	v_cvt_pk_bf16_f32 v144, v145, v147
	v_cvt_pk_bf16_f32 v145, v149, v151
	v_cvt_pk_bf16_f32 v147, v148, v150
	v_mov_b32_e32 v146, v127
	global_store_dwordx2 v[128:129], v[146:147], off offset:128
	global_store_dwordx2 v[128:129], v[144:145], off offset:160
	global_store_dwordx2 v[128:129], v[146:147], off offset:320
	global_store_dwordx2 v[128:129], v[144:145], off offset:352
	global_store_dwordx2 v[128:129], v[146:147], off offset:512
	global_store_dwordx2 v[128:129], v[144:145], off offset:544
	global_store_dwordx2 v[128:129], v[146:147], off offset:704
	global_store_dwordx2 v[128:129], v[144:145], off offset:736

; DI void phase_inproj(const Prm& p, unsigned char* smem_raw, int l, int S, int& base) {
;     ...
;               } else if (nb < 4192) {
;                 if (nb == 4160) {
;                   const f32x4 v2 = acc[ai][bj][(m + 1) & 3][n];
;                   const int pos = tok & (S - 1);
; #pragma unroll
;                   for (int j = 0; j < 4; ++j) {
;                     const int ii = fq * 4 + j;
;                     const float2 cs = p.rope[pos * 16 + ii];
;                     const u16 o1 = f2bf(v[j] * cs.x - v2[j] * cs.y), o2 = f2bf(v[j] * cs.y + v2[j] * cs.x);
; #pragma unroll
;                     for (int hh = 0; hh < 4; ++hh) {
;                       p.kc[(size_t)tok * 384 + hh * 96 + 64 + ii] = o1;
;                       p.kc[(size_t)tok * 384 + hh * 96 + 80 + ii] = o2;
;                     }
;                   }
;                 }
.LBB0_1162:
	s_andn2_b64 vcc, exec, s[52:53]
	s_cbranch_vccnz .LBB0_1165
	s_andn2_b64 vcc, exec, s[4:5]
	s_cbranch_vccnz .LBB0_1165
	v_readlane_b32 s36, v252, 0
	v_readlane_b32 s8, v254, 45
	v_readlane_b32 s37, v252, 1
	v_readlane_b32 s38, v252, 2
	v_readlane_b32 s39, v252, 3
	v_readlane_b32 s40, v252, 4
	v_readlane_b32 s41, v252, 5
	v_readlane_b32 s42, v252, 6
	v_readlane_b32 s43, v252, 7
	v_and_b32_e32 v123, s8, v122
	v_mov_b64_e32 v[124:125], s[36:37]
	v_readlane_b32 s36, v253, 8
	v_lshl_or_b32 v128, v123, 4, v132
	v_mov_b32_e32 v129, v1
	v_readlane_b32 s40, v253, 12
	v_readlane_b32 s41, v253, 13
	v_mad_i64_i32 v[124:125], s[52:53], v122, s33, v[124:125]
	s_nop 0
	v_lshl_add_u64 v[128:129], v[128:129], 3, s[40:41]
	global_load_dwordx2 v[144:145], v[128:129], off
	global_load_dwordx2 v[146:147], v[128:129], off offset:8
	global_load_dwordx2 v[148:149], v[128:129], off offset:16
	global_load_dwordx2 v[150:151], v[128:129], off offset:24
	v_readlane_b32 s37, v253, 9
	v_readlane_b32 s38, v253, 10
	v_readlane_b32 s39, v253, 11
	v_readlane_b32 s42, v253, 14
	v_readlane_b32 s43, v253, 15
	v_readlane_b32 s44, v253, 16
	v_readlane_b32 s45, v253, 17
	v_readlane_b32 s46, v253, 18
	v_readlane_b32 s47, v253, 19
	v_readlane_b32 s48, v253, 20
	v_readlane_b32 s49, v253, 21
	v_readlane_b32 s50, v253, 22
	v_readlane_b32 s51, v253, 23
	s_waitcnt vmcnt(0)
	v_lshlrev_b32_e32 v128, 1, v132
	v_mov_b32_e32 v129, v1
	v_lshl_add_u64 v[124:125], v[124:125], 0, v[128:129]
	v_mul_f32_e32 v123, v102, v145
	v_mul_f32_e32 v145, v118, v145
	v_fmac_f32_e32 v145, v102, v144
	v_fma_f32 v144, v118, v144, -v123
	v_mul_f32_e32 v123, v103, v147
	v_mul_f32_e32 v147, v119, v147
	v_fmac_f32_e32 v147, v103, v146
	v_fma_f32 v146, v119, v146, -v123
	v_mul_f32_e32 v123, v104, v149
	v_mul_f32_e32 v149, v120, v149
	v_fmac_f32_e32 v149, v104, v148
	v_fma_f32 v148, v120, v148, -v123
	v_mul_f32_e32 v123, v105, v151
	v_mul_f32_e32 v151, v121, v151
	v_fmac_f32_e32 v151, v105, v150
	v_fma_f32 v150, v121, v150, -v123
	v_cvt_pk_bf16_f32 v123, v144, v146
	v_cvt_pk_bf16_f32 v144, v145, v147
	v_cvt_pk_bf16_f32 v145, v149, v151
	v_cvt_pk_bf16_f32 v147, v148, v150
	v_mov_b32_e32 v146, v123
	global_store_dwordx2 v[124:125], v[146:147], off offset:128
	global_store_dwordx2 v[124:125], v[144:145], off offset:160
	global_store_dwordx2 v[124:125], v[146:147], off offset:320
	global_store_dwordx2 v[124:125], v[144:145], off offset:352
	global_store_dwordx2 v[124:125], v[146:147], off offset:512
	global_store_dwordx2 v[124:125], v[144:145], off offset:544
	global_store_dwordx2 v[124:125], v[146:147], off offset:704
	global_store_dwordx2 v[124:125], v[144:145], off offset:736

; DI void phase_inproj(const Prm& p, unsigned char* smem_raw, int l, int S, int& base) {
;     ...
;               } else if (nb < 4192) {
;                 if (nb == 4160) {
;                   const f32x4 v2 = acc[ai][bj][(m + 1) & 3][n];
;                   const int pos = tok & (S - 1);
; #pragma unroll
;                   for (int j = 0; j < 4; ++j) {
;                     const int ii = fq * 4 + j;
;                     const float2 cs = p.rope[pos * 16 + ii];
;                     const u16 o1 = f2bf(v[j] * cs.x - v2[j] * cs.y), o2 = f2bf(v[j] * cs.y + v2[j] * cs.x);
; #pragma unroll
;                     for (int hh = 0; hh < 4; ++hh) {
;                       p.kc[(size_t)tok * 384 + hh * 96 + 64 + ii] = o1;
;                       p.kc[(size_t)tok * 384 + hh * 96 + 80 + ii] = o2;
;                     }
;                   }
;                 }
.LBB0_1401:
	s_andn2_b64 vcc, exec, s[54:55]
	s_cbranch_vccnz .LBB0_1404
	s_andn2_b64 vcc, exec, s[4:5]
	s_cbranch_vccnz .LBB0_1404
	v_readlane_b32 s36, v252, 0
	v_readlane_b32 s8, v254, 45
	v_readlane_b32 s37, v252, 1
	v_readlane_b32 s38, v252, 2
	v_readlane_b32 s39, v252, 3
	v_readlane_b32 s40, v252, 4
	v_readlane_b32 s41, v252, 5
	v_readlane_b32 s42, v252, 6
	v_readlane_b32 s43, v252, 7
	v_and_b32_e32 v64, s8, v126
	v_mov_b64_e32 v[62:63], s[36:37]
	v_readlane_b32 s36, v253, 8
	v_lshl_or_b32 v64, v64, 4, v132
	v_mov_b32_e32 v65, v1
	v_readlane_b32 s40, v253, 12
	v_readlane_b32 s41, v253, 13
	v_mad_i64_i32 v[62:63], s[54:55], v126, s33, v[62:63]
	s_nop 0
	v_lshl_add_u64 v[64:65], v[64:65], 3, s[40:41]
	global_load_dwordx2 v[144:145], v[64:65], off
	global_load_dwordx2 v[146:147], v[64:65], off offset:8
	global_load_dwordx2 v[148:149], v[64:65], off offset:16
	global_load_dwordx2 v[150:151], v[64:65], off offset:24
	v_readlane_b32 s37, v253, 9
	v_readlane_b32 s38, v253, 10
	v_readlane_b32 s39, v253, 11
	v_readlane_b32 s42, v253, 14
	v_readlane_b32 s43, v253, 15
	v_readlane_b32 s44, v253, 16
	v_readlane_b32 s45, v253, 17
	v_readlane_b32 s46, v253, 18
	v_readlane_b32 s47, v253, 19
	v_readlane_b32 s48, v253, 20
	v_readlane_b32 s49, v253, 21
	v_readlane_b32 s50, v253, 22
	v_readlane_b32 s51, v253, 23
	s_waitcnt vmcnt(0)
	v_lshlrev_b32_e32 v64, 1, v132
	v_mov_b32_e32 v65, v1
	v_lshl_add_u64 v[62:63], v[62:63], 0, v[64:65]
	v_mul_f32_e32 v72, v42, v145
	v_mul_f32_e32 v145, v58, v145
	v_fmac_f32_e32 v145, v42, v144
	v_fma_f32 v144, v58, v144, -v72
	v_mul_f32_e32 v72, v43, v147
	v_mul_f32_e32 v147, v59, v147
	v_fmac_f32_e32 v147, v43, v146
	v_fma_f32 v146, v59, v146, -v72
	v_mul_f32_e32 v72, v44, v149
	v_mul_f32_e32 v149, v60, v149
	v_fmac_f32_e32 v149, v44, v148
	v_fma_f32 v148, v60, v148, -v72
	v_mul_f32_e32 v72, v45, v151
	v_mul_f32_e32 v151, v61, v151
	v_fmac_f32_e32 v151, v45, v150
	v_fma_f32 v150, v61, v150, -v72
	v_cvt_pk_bf16_f32 v72, v144, v146
	v_cvt_pk_bf16_f32 v144, v145, v147
	v_cvt_pk_bf16_f32 v145, v149, v151
	v_cvt_pk_bf16_f32 v147, v148, v150
	v_mov_b32_e32 v146, v72
	global_store_dwordx2 v[62:63], v[146:147], off offset:128
	global_store_dwordx2 v[62:63], v[144:145], off offset:160
	global_store_dwordx2 v[62:63], v[146:147], off offset:320
	global_store_dwordx2 v[62:63], v[144:145], off offset:352
	global_store_dwordx2 v[62:63], v[146:147], off offset:512
	global_store_dwordx2 v[62:63], v[144:145], off offset:544
	global_store_dwordx2 v[62:63], v[146:147], off offset:704
	global_store_dwordx2 v[62:63], v[144:145], off offset:736

; DI void phase_inproj(const Prm& p, unsigned char* smem_raw, int l, int S, int& base) {
;     ...
;               } else if (nb < 4192) {
;                 if (nb == 4160) {
;                   const f32x4 v2 = acc[ai][bj][(m + 1) & 3][n];
;                   const int pos = tok & (S - 1);
; #pragma unroll
;                   for (int j = 0; j < 4; ++j) {
;                     const int ii = fq * 4 + j;
;                     const float2 cs = p.rope[pos * 16 + ii];
;                     const u16 o1 = f2bf(v[j] * cs.x - v2[j] * cs.y), o2 = f2bf(v[j] * cs.y + v2[j] * cs.x);
; #pragma unroll
;                     for (int hh = 0; hh < 4; ++hh) {
;                       p.kc[(size_t)tok * 384 + hh * 96 + 64 + ii] = o1;
;                       p.kc[(size_t)tok * 384 + hh * 96 + 80 + ii] = o2;
;                     }
;                   }
;                 }
.LBB0_1428:
	s_andn2_b64 vcc, exec, s[54:55]
	s_cbranch_vccnz .LBB0_1431
	s_andn2_b64 vcc, exec, s[4:5]
	s_cbranch_vccnz .LBB0_1431
	v_readlane_b32 s36, v252, 0
	v_readlane_b32 s8, v254, 45
	v_readlane_b32 s37, v252, 1
	v_readlane_b32 s38, v252, 2
	v_readlane_b32 s39, v252, 3
	v_readlane_b32 s40, v252, 4
	v_readlane_b32 s41, v252, 5
	v_readlane_b32 s42, v252, 6
	v_readlane_b32 s43, v252, 7
	v_and_b32_e32 v60, s8, v122
	v_mov_b64_e32 v[58:59], s[36:37]
	v_readlane_b32 s36, v253, 8
	v_lshl_or_b32 v60, v60, 4, v132
	v_mov_b32_e32 v61, v1
	v_readlane_b32 s40, v253, 12
	v_readlane_b32 s41, v253, 13
	v_mad_i64_i32 v[58:59], s[54:55], v122, s33, v[58:59]
	s_nop 0
	v_lshl_add_u64 v[60:61], v[60:61], 3, s[40:41]
	global_load_dwordx2 v[144:145], v[60:61], off
	global_load_dwordx2 v[146:147], v[60:61], off offset:8
	global_load_dwordx2 v[148:149], v[60:61], off offset:16
	global_load_dwordx2 v[150:151], v[60:61], off offset:24
	v_readlane_b32 s37, v253, 9
	v_readlane_b32 s38, v253, 10
	v_readlane_b32 s39, v253, 11
	v_readlane_b32 s42, v253, 14
	v_readlane_b32 s43, v253, 15
	v_readlane_b32 s44, v253, 16
	v_readlane_b32 s45, v253, 17
	v_readlane_b32 s46, v253, 18
	v_readlane_b32 s47, v253, 19
	v_readlane_b32 s48, v253, 20
	v_readlane_b32 s49, v253, 21
	v_readlane_b32 s50, v253, 22
	v_readlane_b32 s51, v253, 23
	s_waitcnt vmcnt(0)
	v_lshlrev_b32_e32 v60, 1, v132
	v_mov_b32_e32 v61, v1
	v_lshl_add_u64 v[58:59], v[58:59], 0, v[60:61]
	v_mul_f32_e32 v64, v38, v145
	v_mul_f32_e32 v145, v54, v145
	v_fmac_f32_e32 v145, v38, v144
	v_fma_f32 v144, v54, v144, -v64
	v_mul_f32_e32 v64, v39, v147
	v_mul_f32_e32 v147, v55, v147
	v_fmac_f32_e32 v147, v39, v146
	v_fma_f32 v146, v55, v146, -v64
	v_mul_f32_e32 v64, v40, v149
	v_mul_f32_e32 v149, v56, v149
	v_fmac_f32_e32 v149, v40, v148
	v_fma_f32 v148, v56, v148, -v64
	v_mul_f32_e32 v64, v41, v151
	v_mul_f32_e32 v151, v57, v151
	v_fmac_f32_e32 v151, v41, v150
	v_fma_f32 v150, v57, v150, -v64
	v_cvt_pk_bf16_f32 v64, v144, v146
	v_cvt_pk_bf16_f32 v144, v145, v147
	v_cvt_pk_bf16_f32 v145, v149, v151
	v_cvt_pk_bf16_f32 v147, v148, v150
	v_mov_b32_e32 v146, v64
	global_store_dwordx2 v[58:59], v[146:147], off offset:128
	global_store_dwordx2 v[58:59], v[144:145], off offset:160
	global_store_dwordx2 v[58:59], v[146:147], off offset:320
	global_store_dwordx2 v[58:59], v[144:145], off offset:352
	global_store_dwordx2 v[58:59], v[146:147], off offset:512
	global_store_dwordx2 v[58:59], v[144:145], off offset:544
	global_store_dwordx2 v[58:59], v[146:147], off offset:704
	global_store_dwordx2 v[58:59], v[144:145], off offset:736

; DI void phase_inproj(const Prm& p, unsigned char* smem_raw, int l, int S, int& base) {
;     ...
;               } else if (nb < 4192) {
;                 if (nb == 4160) {
;                   const f32x4 v2 = acc[ai][bj][(m + 1) & 3][n];
;                   const int pos = tok & (S - 1);
; #pragma unroll
;                   for (int j = 0; j < 4; ++j) {
;                     const int ii = fq * 4 + j;
;                     const float2 cs = p.rope[pos * 16 + ii];
;                     const u16 o1 = f2bf(v[j] * cs.x - v2[j] * cs.y), o2 = f2bf(v[j] * cs.y + v2[j] * cs.x);
; #pragma unroll
;                     for (int hh = 0; hh < 4; ++hh) {
;                       p.kc[(size_t)tok * 384 + hh * 96 + 64 + ii] = o1;
;                       p.kc[(size_t)tok * 384 + hh * 96 + 80 + ii] = o2;
;                     }
;                   }
;                 }
.LBB0_1455:
	s_andn2_b64 vcc, exec, s[2:3]
	s_cbranch_vccnz .LBB0_1458
	s_andn2_b64 vcc, exec, s[4:5]
	s_cbranch_vccnz .LBB0_1458
	v_readlane_b32 s36, v252, 0
	v_readlane_b32 s2, v254, 45
	v_readlane_b32 s37, v252, 1
	v_readlane_b32 s38, v252, 2
	v_readlane_b32 s39, v252, 3
	v_readlane_b32 s40, v252, 4
	v_readlane_b32 s41, v252, 5
	v_readlane_b32 s42, v252, 6
	v_readlane_b32 s43, v252, 7
	v_and_b32_e32 v56, s2, v118
	v_mov_b64_e32 v[54:55], s[36:37]
	v_readlane_b32 s36, v253, 8
	v_lshl_or_b32 v56, v56, 4, v132
	v_mov_b32_e32 v57, v1
	v_readlane_b32 s40, v253, 12
	v_readlane_b32 s41, v253, 13
	v_mad_i64_i32 v[54:55], s[2:3], v118, s33, v[54:55]
	s_nop 0
	v_lshl_add_u64 v[56:57], v[56:57], 3, s[40:41]
	global_load_dwordx2 v[144:145], v[56:57], off
	global_load_dwordx2 v[146:147], v[56:57], off offset:8
	global_load_dwordx2 v[148:149], v[56:57], off offset:16
	global_load_dwordx2 v[150:151], v[56:57], off offset:24
	v_readlane_b32 s37, v253, 9
	v_readlane_b32 s38, v253, 10
	v_readlane_b32 s39, v253, 11
	v_readlane_b32 s42, v253, 14
	v_readlane_b32 s43, v253, 15
	v_readlane_b32 s44, v253, 16
	v_readlane_b32 s45, v253, 17
	v_readlane_b32 s46, v253, 18
	v_readlane_b32 s47, v253, 19
	v_readlane_b32 s48, v253, 20
	v_readlane_b32 s49, v253, 21
	v_readlane_b32 s50, v253, 22
	v_readlane_b32 s51, v253, 23
	s_waitcnt vmcnt(0)
	v_lshlrev_b32_e32 v56, 1, v132
	v_mov_b32_e32 v57, v1
	v_lshl_add_u64 v[54:55], v[54:55], 0, v[56:57]
	v_mul_f32_e32 v60, v34, v145
	v_mul_f32_e32 v145, v50, v145
	v_fmac_f32_e32 v145, v34, v144
	v_fma_f32 v144, v50, v144, -v60
	v_mul_f32_e32 v60, v35, v147
	v_mul_f32_e32 v147, v51, v147
	v_fmac_f32_e32 v147, v35, v146
	v_fma_f32 v146, v51, v146, -v60
	v_mul_f32_e32 v60, v36, v149
	v_mul_f32_e32 v149, v52, v149
	v_fmac_f32_e32 v149, v36, v148
	v_fma_f32 v148, v52, v148, -v60
	v_mul_f32_e32 v60, v37, v151
	v_mul_f32_e32 v151, v53, v151
	v_fmac_f32_e32 v151, v37, v150
	v_fma_f32 v150, v53, v150, -v60
	v_cvt_pk_bf16_f32 v60, v144, v146
	v_cvt_pk_bf16_f32 v144, v145, v147
	v_cvt_pk_bf16_f32 v145, v149, v151
	v_cvt_pk_bf16_f32 v147, v148, v150
	v_mov_b32_e32 v146, v60
	global_store_dwordx2 v[54:55], v[146:147], off offset:128
	global_store_dwordx2 v[54:55], v[144:145], off offset:160
	global_store_dwordx2 v[54:55], v[146:147], off offset:320
	global_store_dwordx2 v[54:55], v[144:145], off offset:352
	global_store_dwordx2 v[54:55], v[146:147], off offset:512
	global_store_dwordx2 v[54:55], v[144:145], off offset:544
	global_store_dwordx2 v[54:55], v[146:147], off offset:704
	global_store_dwordx2 v[54:55], v[144:145], off offset:736
